# P8 top-k: score values of each head requested one head ahead into spare registers
# baseline (speedup 1.0000x reference)
.LBB0_922:
	s_waitcnt lgkmcnt(0)
	v_lshl_add_u64 v[2:3], v[0:1], 0, s[64:65]
	v_add_co_u32_e32 v60, vcc, 0x8008000, v2
	s_nop 1
	v_addc_co_u32_e32 v61, vcc, 0, v3, vcc
	s_cmp_eq_u32 s64, 0
	s_cbranch_scc0 .Lpf_have
	global_load_dword v128, v[60:61], off
	global_load_dword v129, v[60:61], off offset:256
	global_load_dword v130, v[60:61], off offset:512
	global_load_dword v131, v[60:61], off offset:768
.Lpf_have:
	global_load_dword v132, v[60:61], off offset:1024
	global_load_dword v133, v[60:61], off offset:1280
	global_load_dword v134, v[60:61], off offset:1536
	global_load_dword v135, v[60:61], off offset:1792
	s_waitcnt vmcnt(4)
	v_mov_b32_e32 v59, v128
	v_mov_b32_e32 v62, v129
	v_mov_b32_e32 v63, v130
	v_mov_b32_e32 v60, v131
	v_ashrrev_i32_e32 v61, 31, v59
	v_and_b32_e32 v64, 0xffffff80, v59
	v_ashrrev_i32_e32 v65, 31, v62
	v_ashrrev_i32_e32 v67, 31, v63
	v_and_b32_e32 v61, 0x7fffff80, v61
	v_and_b32_e32 v66, 0xffffff80, v62
	v_and_b32_e32 v68, 0xffffff80, v63
	v_and_b32_e32 v65, 0x7fffff80, v65
	v_and_b32_e32 v67, 0x7fffff80, v67
	v_bitop3_b32 v61, v61, v164, v64 bitop3:0xde
	v_bitop3_b32 v64, v65, v165, v66 bitop3:0xde
	v_bitop3_b32 v65, v67, v164, v68 bitop3:0xde
	v_mov_b32_dpp v67, v61 quad_perm:[1,0,3,2] row_mask:0xf bank_mask:0xf bound_ctrl:1
	v_mov_b32_dpp v68, v64 quad_perm:[1,0,3,2] row_mask:0xf bank_mask:0xf bound_ctrl:1
	v_med3_i32 v61, v61, v67, v100
	v_med3_i32 v64, v64, v68, v100
	v_ashrrev_i32_e32 v69, 31, v60
	v_mov_b32_dpp v67, v61 quad_perm:[2,3,0,1] row_mask:0xf bank_mask:0xf bound_ctrl:1
	v_mov_b32_dpp v68, v64 quad_perm:[2,3,0,1] row_mask:0xf bank_mask:0xf bound_ctrl:1
	v_med3_i32 v61, v61, v67, v101
	v_med3_i32 v64, v64, v68, v101
	v_and_b32_e32 v70, 0xffffff80, v60
	v_mov_b32_dpp v67, v61 quad_perm:[1,0,3,2] row_mask:0xf bank_mask:0xf bound_ctrl:1
	v_mov_b32_dpp v68, v64 quad_perm:[1,0,3,2] row_mask:0xf bank_mask:0xf bound_ctrl:1
	v_med3_i32 v61, v61, v67, v102
	v_and_b32_e32 v69, 0x7fffff80, v69
	v_med3_i32 v64, v64, v68, v102
	v_mov_b32_dpp v67, v61 row_half_mirror row_mask:0xf bank_mask:0xf bound_ctrl:1
	v_bitop3_b32 v66, v69, v165, v70 bitop3:0xde
	v_mov_b32_dpp v68, v64 row_half_mirror row_mask:0xf bank_mask:0xf bound_ctrl:1
	v_mov_b32_dpp v69, v67 quad_perm:[3,2,1,0] row_mask:0xf bank_mask:0xf bound_ctrl:1
	s_nop 0
	v_mov_b32_dpp v67, v68 quad_perm:[3,2,1,0] row_mask:0xf bank_mask:0xf bound_ctrl:1
	v_med3_i32 v61, v61, v69, v103
	v_med3_i32 v64, v64, v67, v103
	s_nop 0
	v_mov_b32_dpp v67, v61 quad_perm:[2,3,0,1] row_mask:0xf bank_mask:0xf bound_ctrl:1
	v_mov_b32_dpp v68, v64 quad_perm:[2,3,0,1] row_mask:0xf bank_mask:0xf bound_ctrl:1
	v_med3_i32 v61, v61, v67, v104
	v_med3_i32 v64, v64, v68, v104
	s_nop 0
	v_mov_b32_dpp v67, v61 quad_perm:[1,0,3,2] row_mask:0xf bank_mask:0xf bound_ctrl:1
	v_mov_b32_dpp v68, v64 quad_perm:[1,0,3,2] row_mask:0xf bank_mask:0xf bound_ctrl:1
	v_med3_i32 v61, v61, v67, v105
	v_med3_i32 v64, v64, v68, v105
	s_nop 0
	v_mov_b32_dpp v67, v61 row_ror:8 row_mask:0xf bank_mask:0xf bound_ctrl:1
	v_mov_b32_dpp v68, v64 row_ror:8 row_mask:0xf bank_mask:0xf bound_ctrl:1
	v_med3_i32 v61, v61, v67, v106
	v_med3_i32 v64, v64, v68, v106
	s_nop 0
	v_mov_b32_dpp v67, v61 row_half_mirror row_mask:0xf bank_mask:0xf bound_ctrl:1
	v_mov_b32_dpp v68, v64 row_half_mirror row_mask:0xf bank_mask:0xf bound_ctrl:1
	s_nop 0
	v_mov_b32_dpp v69, v67 quad_perm:[3,2,1,0] row_mask:0xf bank_mask:0xf bound_ctrl:1
	v_mov_b32_dpp v67, v68 quad_perm:[3,2,1,0] row_mask:0xf bank_mask:0xf bound_ctrl:1
	v_med3_i32 v61, v61, v69, v107
	v_med3_i32 v64, v64, v67, v107
	s_nop 0
	v_mov_b32_dpp v67, v61 quad_perm:[2,3,0,1] row_mask:0xf bank_mask:0xf bound_ctrl:1
	v_mov_b32_dpp v68, v64 quad_perm:[2,3,0,1] row_mask:0xf bank_mask:0xf bound_ctrl:1
	v_med3_i32 v61, v61, v67, v108
	v_med3_i32 v64, v64, v68, v108
	s_nop 0
	v_mov_b32_dpp v67, v61 quad_perm:[1,0,3,2] row_mask:0xf bank_mask:0xf bound_ctrl:1
	v_mov_b32_dpp v68, v64 quad_perm:[1,0,3,2] row_mask:0xf bank_mask:0xf bound_ctrl:1
	v_med3_i32 v61, v61, v67, v109
	v_med3_i32 v64, v64, v68, v109
	v_mov_b32_e32 v67, v61
	v_mov_b32_e32 v68, v61
	v_mov_b32_e32 v69, v64
	v_mov_b32_e32 v70, v64
	v_permlane16_swap_b32_e32 v67, v68
	s_nop 0
	v_permlane16_swap_b32_e32 v69, v70
	v_cndmask_b32_e64 v67, v67, v68, s[6:7]
	v_cndmask_b32_e64 v68, v69, v70, s[6:7]
	v_max_i32_e32 v69, v61, v67
	v_min_i32_e32 v61, v61, v67
	v_cndmask_b32_e64 v61, v61, v69, s[42:43]
	v_med3_i32 v64, v64, v68, v110
	s_nop 0
	v_mov_b32_dpp v67, v61 row_ror:8 row_mask:0xf bank_mask:0xf bound_ctrl:1
	v_mov_b32_dpp v68, v64 row_ror:8 row_mask:0xf bank_mask:0xf bound_ctrl:1
	v_med3_i32 v61, v61, v67, v111
	v_med3_i32 v64, v64, v68, v111
	s_nop 0
	v_mov_b32_dpp v67, v61 row_half_mirror row_mask:0xf bank_mask:0xf bound_ctrl:1
	v_mov_b32_dpp v68, v64 row_half_mirror row_mask:0xf bank_mask:0xf bound_ctrl:1
	s_nop 0
	v_mov_b32_dpp v69, v67 quad_perm:[3,2,1,0] row_mask:0xf bank_mask:0xf bound_ctrl:1
	v_mov_b32_dpp v67, v68 quad_perm:[3,2,1,0] row_mask:0xf bank_mask:0xf bound_ctrl:1
	v_med3_i32 v61, v61, v69, v112
	v_med3_i32 v64, v64, v67, v112
	s_nop 0
	v_mov_b32_dpp v67, v61 quad_perm:[2,3,0,1] row_mask:0xf bank_mask:0xf bound_ctrl:1
	v_med3_i32 v61, v61, v67, v113
	v_mov_b32_dpp v67, v64 quad_perm:[2,3,0,1] row_mask:0xf bank_mask:0xf bound_ctrl:1
	v_med3_i32 v64, v64, v67, v113
	v_mov_b32_dpp v67, v61 quad_perm:[1,0,3,2] row_mask:0xf bank_mask:0xf bound_ctrl:1
	v_med3_i32 v61, v61, v67, v114
	v_mov_b32_dpp v67, v64 quad_perm:[1,0,3,2] row_mask:0xf bank_mask:0xf bound_ctrl:1
	v_med3_i32 v64, v64, v67, v114
	v_mov_b32_e32 v68, v61
	s_nop 1
	v_permlane32_swap_b32_e32 v61, v68
	v_med3_i32 v61, v61, v68, v115
	v_mov_b32_e32 v69, v64
	s_nop 1
	v_permlane32_swap_b32_e32 v64, v69
	v_med3_i32 v64, v64, v69, v116
	v_mov_b32_e32 v68, v61
	s_nop 1
	v_permlane16_swap_b32_e32 v61, v68
	v_med3_i32 v61, v61, v68, v117
	v_mov_b32_e32 v69, v64
	s_nop 1
	v_permlane16_swap_b32_e32 v64, v69
	v_med3_i32 v64, v64, v69, v118
	s_nop 0
	v_mov_b32_dpp v67, v61 row_ror:8 row_mask:0xf bank_mask:0xf bound_ctrl:1
	v_med3_i32 v61, v61, v67, v119
	v_mov_b32_dpp v67, v64 row_ror:8 row_mask:0xf bank_mask:0xf bound_ctrl:1
	v_med3_i32 v64, v64, v67, v120
	v_mov_b32_dpp v67, v61 row_half_mirror row_mask:0xf bank_mask:0xf bound_ctrl:1
	s_nop 0
	v_mov_b32_dpp v68, v64 row_half_mirror row_mask:0xf bank_mask:0xf bound_ctrl:1
	v_mov_b32_dpp v69, v67 quad_perm:[3,2,1,0] row_mask:0xf bank_mask:0xf bound_ctrl:1
	v_med3_i32 v61, v61, v69, v121
	v_mov_b32_dpp v67, v68 quad_perm:[3,2,1,0] row_mask:0xf bank_mask:0xf bound_ctrl:1
	v_med3_i32 v64, v64, v67, v122
	v_mov_b32_dpp v67, v61 quad_perm:[2,3,0,1] row_mask:0xf bank_mask:0xf bound_ctrl:1
	v_med3_i32 v61, v61, v67, v123
	v_mov_b32_dpp v67, v64 quad_perm:[2,3,0,1] row_mask:0xf bank_mask:0xf bound_ctrl:1
	v_med3_i32 v64, v64, v67, v124
	v_mov_b32_dpp v67, v61 quad_perm:[1,0,3,2] row_mask:0xf bank_mask:0xf bound_ctrl:1
	v_med3_i32 v61, v61, v67, v125
	v_mov_b32_dpp v67, v64 quad_perm:[1,0,3,2] row_mask:0xf bank_mask:0xf bound_ctrl:1
	v_med3_i32 v64, v64, v67, v126
	v_max_i32_e32 v61, v61, v64
	v_mov_b32_e32 v67, v61
	s_nop 1
	v_permlane32_swap_b32_e32 v61, v67
	v_med3_i32 v61, v61, v67, v127
	v_mov_b32_e32 v67, v61
	s_nop 1
	v_permlane16_swap_b32_e32 v61, v67
	v_med3_i32 v61, v61, v67, v117
	s_nop 1
	v_mov_b32_dpp v64, v61 row_ror:8 row_mask:0xf bank_mask:0xf bound_ctrl:1
	v_med3_i32 v61, v61, v64, v119
	s_nop 1
	v_mov_b32_dpp v64, v61 row_half_mirror row_mask:0xf bank_mask:0xf bound_ctrl:1
	s_nop 1
	v_mov_b32_dpp v67, v64 quad_perm:[3,2,1,0] row_mask:0xf bank_mask:0xf bound_ctrl:1
	v_med3_i32 v61, v61, v67, v121
	s_nop 1
	v_mov_b32_dpp v64, v61 quad_perm:[2,3,0,1] row_mask:0xf bank_mask:0xf bound_ctrl:1
	v_med3_i32 v61, v61, v64, v123
	s_nop 1
	v_mov_b32_dpp v64, v61 quad_perm:[1,0,3,2] row_mask:0xf bank_mask:0xf bound_ctrl:1
	v_med3_i32 v61, v61, v64, v125
	v_max_i32_dpp v64, v65, v65 quad_perm:[1,0,3,2] row_mask:0xf bank_mask:0xf bound_ctrl:1
	v_min_i32_dpp v65, v65, v65 quad_perm:[1,0,3,2] row_mask:0xf bank_mask:0xf bound_ctrl:1
	v_cndmask_b32_e64 v64, v65, v64, s[12:13]
	s_nop 0
	v_max_i32_dpp v65, v66, v66 quad_perm:[1,0,3,2] row_mask:0xf bank_mask:0xf bound_ctrl:1
	v_min_i32_dpp v66, v66, v66 quad_perm:[1,0,3,2] row_mask:0xf bank_mask:0xf bound_ctrl:1
	v_cndmask_b32_e64 v65, v66, v65, s[12:13]
	s_nop 0
	v_mov_b32_dpp v66, v64 quad_perm:[2,3,0,1] row_mask:0xf bank_mask:0xf bound_ctrl:1
	v_med3_i32 v64, v64, v66, v101
	v_mov_b32_dpp v66, v65 quad_perm:[2,3,0,1] row_mask:0xf bank_mask:0xf bound_ctrl:1
	v_med3_i32 v65, v65, v66, v101
	v_mov_b32_dpp v66, v64 quad_perm:[1,0,3,2] row_mask:0xf bank_mask:0xf bound_ctrl:1
	v_med3_i32 v64, v64, v66, v102
	v_mov_b32_dpp v66, v65 quad_perm:[1,0,3,2] row_mask:0xf bank_mask:0xf bound_ctrl:1
	v_med3_i32 v65, v65, v66, v102
	v_mov_b32_dpp v66, v64 row_half_mirror row_mask:0xf bank_mask:0xf bound_ctrl:1
	s_nop 0
	v_mov_b32_dpp v67, v65 row_half_mirror row_mask:0xf bank_mask:0xf bound_ctrl:1
	v_mov_b32_dpp v68, v66 quad_perm:[3,2,1,0] row_mask:0xf bank_mask:0xf bound_ctrl:1
	v_med3_i32 v64, v64, v68, v103
	v_mov_b32_dpp v66, v67 quad_perm:[3,2,1,0] row_mask:0xf bank_mask:0xf bound_ctrl:1
	v_med3_i32 v65, v65, v66, v103
	v_mov_b32_dpp v66, v64 quad_perm:[2,3,0,1] row_mask:0xf bank_mask:0xf bound_ctrl:1
	v_med3_i32 v64, v64, v66, v104
	v_mov_b32_dpp v66, v65 quad_perm:[2,3,0,1] row_mask:0xf bank_mask:0xf bound_ctrl:1
	v_med3_i32 v65, v65, v66, v104
	v_mov_b32_dpp v66, v64 quad_perm:[1,0,3,2] row_mask:0xf bank_mask:0xf bound_ctrl:1
	v_med3_i32 v64, v64, v66, v105
	v_mov_b32_dpp v66, v65 quad_perm:[1,0,3,2] row_mask:0xf bank_mask:0xf bound_ctrl:1
	v_med3_i32 v65, v65, v66, v105
	v_mov_b32_dpp v66, v64 row_ror:8 row_mask:0xf bank_mask:0xf bound_ctrl:1
	v_med3_i32 v64, v64, v66, v106
	v_mov_b32_dpp v66, v65 row_ror:8 row_mask:0xf bank_mask:0xf bound_ctrl:1
	v_med3_i32 v65, v65, v66, v106
	v_mov_b32_dpp v66, v64 row_half_mirror row_mask:0xf bank_mask:0xf bound_ctrl:1
	s_nop 0
	v_mov_b32_dpp v67, v65 row_half_mirror row_mask:0xf bank_mask:0xf bound_ctrl:1
	v_mov_b32_dpp v68, v66 quad_perm:[3,2,1,0] row_mask:0xf bank_mask:0xf bound_ctrl:1
	v_med3_i32 v64, v64, v68, v107
	v_mov_b32_dpp v66, v67 quad_perm:[3,2,1,0] row_mask:0xf bank_mask:0xf bound_ctrl:1
	v_med3_i32 v65, v65, v66, v107
	v_mov_b32_dpp v66, v64 quad_perm:[2,3,0,1] row_mask:0xf bank_mask:0xf bound_ctrl:1
	v_med3_i32 v64, v64, v66, v108
	v_mov_b32_dpp v66, v65 quad_perm:[2,3,0,1] row_mask:0xf bank_mask:0xf bound_ctrl:1
	v_med3_i32 v65, v65, v66, v108
	v_mov_b32_dpp v66, v64 quad_perm:[1,0,3,2] row_mask:0xf bank_mask:0xf bound_ctrl:1
	v_med3_i32 v64, v64, v66, v109
	v_mov_b32_dpp v66, v65 quad_perm:[1,0,3,2] row_mask:0xf bank_mask:0xf bound_ctrl:1
	v_med3_i32 v65, v65, v66, v109
	v_mov_b32_e32 v67, v64
	s_nop 1
	v_permlane16_swap_b32_e32 v64, v67
	v_med3_i32 v64, v64, v67, v110
	v_mov_b32_e32 v68, v65
	s_nop 1
	v_permlane16_swap_b32_e32 v65, v68
	v_med3_i32 v65, v65, v68, v110
	s_nop 0
	v_mov_b32_dpp v66, v64 row_ror:8 row_mask:0xf bank_mask:0xf bound_ctrl:1
	v_med3_i32 v64, v64, v66, v111
	v_mov_b32_dpp v66, v65 row_ror:8 row_mask:0xf bank_mask:0xf bound_ctrl:1
	v_med3_i32 v65, v65, v66, v111
	v_mov_b32_dpp v66, v64 row_half_mirror row_mask:0xf bank_mask:0xf bound_ctrl:1
	s_nop 0
	v_mov_b32_dpp v67, v65 row_half_mirror row_mask:0xf bank_mask:0xf bound_ctrl:1
	v_mov_b32_dpp v68, v66 quad_perm:[3,2,1,0] row_mask:0xf bank_mask:0xf bound_ctrl:1
	v_med3_i32 v64, v64, v68, v112
	v_mov_b32_dpp v66, v67 quad_perm:[3,2,1,0] row_mask:0xf bank_mask:0xf bound_ctrl:1
	v_med3_i32 v65, v65, v66, v112
	v_mov_b32_dpp v66, v64 quad_perm:[2,3,0,1] row_mask:0xf bank_mask:0xf bound_ctrl:1
	v_med3_i32 v64, v64, v66, v113
	v_mov_b32_dpp v66, v65 quad_perm:[2,3,0,1] row_mask:0xf bank_mask:0xf bound_ctrl:1
	v_med3_i32 v65, v65, v66, v113
	v_mov_b32_dpp v66, v64 quad_perm:[1,0,3,2] row_mask:0xf bank_mask:0xf bound_ctrl:1
	v_med3_i32 v64, v64, v66, v114
	v_mov_b32_dpp v66, v65 quad_perm:[1,0,3,2] row_mask:0xf bank_mask:0xf bound_ctrl:1
	v_med3_i32 v65, v65, v66, v114
	v_mov_b32_e32 v67, v64
	s_nop 1
	v_permlane32_swap_b32_e32 v64, v67
	v_med3_i32 v64, v64, v67, v115
	v_mov_b32_e32 v68, v65
	s_nop 1
	v_permlane32_swap_b32_e32 v65, v68
	v_med3_i32 v65, v65, v68, v116
	v_mov_b32_e32 v67, v64
	s_nop 1
	v_permlane16_swap_b32_e32 v64, v67
	v_med3_i32 v64, v64, v67, v117
	v_mov_b32_e32 v68, v65
	s_nop 1
	v_permlane16_swap_b32_e32 v65, v68
	v_med3_i32 v65, v65, v68, v118
	s_nop 0
	v_mov_b32_dpp v66, v64 row_ror:8 row_mask:0xf bank_mask:0xf bound_ctrl:1
	v_med3_i32 v64, v64, v66, v119
	v_mov_b32_dpp v66, v65 row_ror:8 row_mask:0xf bank_mask:0xf bound_ctrl:1
	v_med3_i32 v65, v65, v66, v120
	v_mov_b32_dpp v66, v64 row_half_mirror row_mask:0xf bank_mask:0xf bound_ctrl:1
	s_nop 0
	v_mov_b32_dpp v67, v65 row_half_mirror row_mask:0xf bank_mask:0xf bound_ctrl:1
	v_mov_b32_dpp v68, v66 quad_perm:[3,2,1,0] row_mask:0xf bank_mask:0xf bound_ctrl:1
	v_med3_i32 v64, v64, v68, v121
	v_mov_b32_dpp v66, v67 quad_perm:[3,2,1,0] row_mask:0xf bank_mask:0xf bound_ctrl:1
	v_med3_i32 v65, v65, v66, v122
	v_mov_b32_dpp v66, v64 quad_perm:[2,3,0,1] row_mask:0xf bank_mask:0xf bound_ctrl:1
	v_med3_i32 v64, v64, v66, v123
	v_mov_b32_dpp v66, v65 quad_perm:[2,3,0,1] row_mask:0xf bank_mask:0xf bound_ctrl:1
	v_med3_i32 v65, v65, v66, v124
	v_mov_b32_dpp v66, v64 quad_perm:[1,0,3,2] row_mask:0xf bank_mask:0xf bound_ctrl:1
	v_med3_i32 v64, v64, v66, v125
	v_mov_b32_dpp v66, v65 quad_perm:[1,0,3,2] row_mask:0xf bank_mask:0xf bound_ctrl:1
	v_med3_i32 v65, v65, v66, v126
	v_max_i32_e32 v64, v64, v65
	v_mov_b32_e32 v66, v64
	s_nop 1
	v_permlane32_swap_b32_e32 v64, v66
	v_med3_i32 v64, v64, v66, v127
	v_mov_b32_e32 v66, v64
	s_nop 1
	v_permlane16_swap_b32_e32 v64, v66
	v_med3_i32 v64, v64, v66, v117
	s_nop 1
	v_mov_b32_dpp v65, v64 row_ror:8 row_mask:0xf bank_mask:0xf bound_ctrl:1
	v_med3_i32 v64, v64, v65, v119
	s_nop 1
	v_mov_b32_dpp v65, v64 row_half_mirror row_mask:0xf bank_mask:0xf bound_ctrl:1
	s_nop 1
	v_mov_b32_dpp v66, v65 quad_perm:[3,2,1,0] row_mask:0xf bank_mask:0xf bound_ctrl:1
	v_med3_i32 v64, v64, v66, v121
	s_nop 1
	v_mov_b32_dpp v65, v64 quad_perm:[2,3,0,1] row_mask:0xf bank_mask:0xf bound_ctrl:1
	v_med3_i32 v64, v64, v65, v123
	s_nop 1
	v_mov_b32_dpp v65, v64 quad_perm:[1,0,3,2] row_mask:0xf bank_mask:0xf bound_ctrl:1
	v_med3_i32 v64, v64, v65, v125
	v_bitop3_b32 v65, v61, s78, v61 bitop3:0xc
	v_bitop3_b32 v61, v61, v166, 63 bitop3:0xce
	v_lshlrev_b32_e32 v61, 2, v61
	ds_bpermute_b32 v59, v61, v59
	ds_bpermute_b32 v61, v61, v62
	v_bitop3_b32 v62, v64, v166, 63 bitop3:0xce
	v_lshlrev_b32_e32 v62, 2, v62
	ds_bpermute_b32 v63, v62, v63
	ds_bpermute_b32 v60, v62, v60
	v_bitop3_b32 v62, v64, s78, v64 bitop3:0xc
	v_cmp_gt_u32_e32 vcc, 64, v65
	s_waitcnt lgkmcnt(2)
	s_nop 0
	v_cndmask_b32_e32 v59, v61, v59, vcc
	v_cmp_gt_u32_e32 vcc, 64, v62
	ds_bpermute_b32 v59, v167, v59
	ds_bpermute_b32 v62, v168, v62
	s_waitcnt lgkmcnt(2)
	v_cndmask_b32_e32 v60, v60, v63, vcc
	ds_bpermute_b32 v60, v168, v60
	s_waitcnt lgkmcnt(0)
	v_add_f32_e32 v59, v59, v60
	v_ashrrev_i32_e32 v60, 31, v59
	v_and_b32_e32 v60, 0x7fffffc0, v60
	v_and_b32_e32 v61, 0xffffffc0, v59
	v_bitop3_b32 v60, v60, v165, v61 bitop3:0xde
	v_cndmask_b32_e64 v60, v60, v173, s[4:5]
	s_nop 1
	v_mov_b32_dpp v61, v60 quad_perm:[1,0,3,2] row_mask:0xf bank_mask:0xf bound_ctrl:1
	v_med3_i32 v60, v60, v61, v100
	s_nop 1
	v_mov_b32_dpp v61, v60 quad_perm:[2,3,0,1] row_mask:0xf bank_mask:0xf bound_ctrl:1
	v_med3_i32 v60, v60, v61, v101
	s_nop 1
	v_mov_b32_dpp v61, v60 quad_perm:[1,0,3,2] row_mask:0xf bank_mask:0xf bound_ctrl:1
	v_med3_i32 v60, v60, v61, v102
	s_nop 1
	v_mov_b32_dpp v61, v60 row_half_mirror row_mask:0xf bank_mask:0xf bound_ctrl:1
	s_nop 1
	v_mov_b32_dpp v63, v61 quad_perm:[3,2,1,0] row_mask:0xf bank_mask:0xf bound_ctrl:1
	v_med3_i32 v60, v60, v63, v103
	s_nop 1
	v_mov_b32_dpp v61, v60 quad_perm:[2,3,0,1] row_mask:0xf bank_mask:0xf bound_ctrl:1
	v_med3_i32 v60, v60, v61, v104
	s_nop 1
	v_mov_b32_dpp v61, v60 quad_perm:[1,0,3,2] row_mask:0xf bank_mask:0xf bound_ctrl:1
	v_med3_i32 v60, v60, v61, v105
	s_nop 1
	v_mov_b32_dpp v61, v60 row_ror:8 row_mask:0xf bank_mask:0xf bound_ctrl:1
	v_med3_i32 v60, v60, v61, v106
	s_nop 1
	v_mov_b32_dpp v61, v60 row_half_mirror row_mask:0xf bank_mask:0xf bound_ctrl:1
	s_nop 1
	v_mov_b32_dpp v63, v61 quad_perm:[3,2,1,0] row_mask:0xf bank_mask:0xf bound_ctrl:1
	v_med3_i32 v60, v60, v63, v107
	s_nop 1
	v_mov_b32_dpp v61, v60 quad_perm:[2,3,0,1] row_mask:0xf bank_mask:0xf bound_ctrl:1
	v_med3_i32 v60, v60, v61, v108
	s_nop 1
	v_mov_b32_dpp v61, v60 quad_perm:[1,0,3,2] row_mask:0xf bank_mask:0xf bound_ctrl:1
	v_med3_i32 v60, v60, v61, v109
	v_mov_b32_e32 v63, v60
	s_nop 1
	v_permlane16_swap_b32_e32 v60, v63
	v_med3_i32 v60, v60, v63, v110
	s_nop 1
	v_mov_b32_dpp v61, v60 row_ror:8 row_mask:0xf bank_mask:0xf bound_ctrl:1
	v_med3_i32 v60, v60, v61, v111
	s_nop 1
	v_mov_b32_dpp v61, v60 row_half_mirror row_mask:0xf bank_mask:0xf bound_ctrl:1
	s_nop 1
	v_mov_b32_dpp v63, v61 quad_perm:[3,2,1,0] row_mask:0xf bank_mask:0xf bound_ctrl:1
	v_med3_i32 v60, v60, v63, v112
	s_nop 1
	v_mov_b32_dpp v61, v60 quad_perm:[2,3,0,1] row_mask:0xf bank_mask:0xf bound_ctrl:1
	v_med3_i32 v60, v60, v61, v113
	s_nop 1
	v_mov_b32_dpp v61, v60 quad_perm:[1,0,3,2] row_mask:0xf bank_mask:0xf bound_ctrl:1
	v_med3_i32 v60, v60, v61, v114
	v_mov_b32_e32 v63, v60
	s_nop 1
	v_permlane32_swap_b32_e32 v60, v63
	v_med3_i32 v60, v60, v63, v127
	v_mov_b32_e32 v63, v60
	s_nop 1
	v_permlane16_swap_b32_e32 v60, v63
	v_med3_i32 v60, v60, v63, v117
	s_nop 1
	v_mov_b32_dpp v61, v60 row_ror:8 row_mask:0xf bank_mask:0xf bound_ctrl:1
	v_med3_i32 v60, v60, v61, v119
	s_nop 1
	v_mov_b32_dpp v61, v60 row_half_mirror row_mask:0xf bank_mask:0xf bound_ctrl:1
	s_nop 1
	v_mov_b32_dpp v63, v61 quad_perm:[3,2,1,0] row_mask:0xf bank_mask:0xf bound_ctrl:1
	v_med3_i32 v60, v60, v63, v121
	s_nop 1
	v_mov_b32_dpp v61, v60 quad_perm:[2,3,0,1] row_mask:0xf bank_mask:0xf bound_ctrl:1
	v_med3_i32 v60, v60, v61, v123
	s_nop 1
	v_mov_b32_dpp v61, v60 quad_perm:[1,0,3,2] row_mask:0xf bank_mask:0xf bound_ctrl:1
	v_med3_i32 v60, v60, v61, v125
	v_and_or_b32 v60, v60, 63, v166
	v_lshlrev_b32_e32 v60, 2, v60
	v_xor_b32_e32 v60, 0xfc, v60
	ds_bpermute_b32 v59, v60, v59
	ds_bpermute_b32 v61, v167, v65
	s_waitcnt lgkmcnt(1)
	v_readlane_b32 s33, v59, 0
	s_nop 1
	v_subrev_f32_e32 v59, s33, v59
	v_mul_f32_e32 v59, v24, v59
	v_mul_f32_e32 v59, 0x3fb8aa3b, v59
	v_exp_f32_e32 v59, v59
	s_waitcnt lgkmcnt(0)
	v_lshl_add_u32 v61, v61, 7, v62
	ds_bpermute_b32 v60, v60, v61
	v_cndmask_b32_e64 v61, 0, v59, s[54:55]
	s_nop 1
	v_add_f32_dpp v61, v61, v61 row_ror:8 row_mask:0xf bank_mask:0xf bound_ctrl:1
	s_nop 1
	v_mov_b32_dpp v62, v61 row_half_mirror row_mask:0xf bank_mask:0xf bound_ctrl:1
	s_nop 1
	v_add_f32_dpp v61, v62, v61 quad_perm:[3,2,1,0] row_mask:0xf bank_mask:0xf bound_ctrl:1
	s_nop 1
	v_add_f32_dpp v61, v61, v61 quad_perm:[2,3,0,1] row_mask:0xf bank_mask:0xf bound_ctrl:1
	s_nop 1
	v_mov_b32_dpp v62, v61 quad_perm:[1,0,3,2] row_mask:0xf bank_mask:0xf bound_ctrl:1
	s_and_saveexec_b64 s[66:67], s[54:55]
	s_cbranch_execz .LBB0_924
	v_add_f32_e32 v61, v61, v62
	v_div_scale_f32 v62, s[68:69], v61, v61, v59
	v_rcp_f32_e32 v63, v62
	v_div_scale_f32 v64, vcc, v59, v61, v59
	v_fma_f32 v65, -v62, v63, 1.0
	v_fmac_f32_e32 v63, v65, v63
	v_mul_f32_e32 v65, v64, v63
	v_fma_f32 v66, -v62, v65, v64
	v_fmac_f32_e32 v65, v66, v63
	v_fma_f32 v62, -v62, v65, v64
	v_div_fmas_f32 v62, v62, v63, v65
	v_div_fixup_f32 v59, v62, v61, v59
	s_waitcnt lgkmcnt(0)
	ds_write2st64_b32 v28, v60, v59 offset1:2
.LBB0_924:
	s_or_b64 exec, exec, s[66:67]
	v_add_co_u32_e32 v2, vcc, 0x8008000, v2
	s_nop 1
	v_addc_co_u32_e32 v3, vcc, 0, v3, vcc
	s_cmp_lt_u32 s64, 0x1800
	s_cbranch_scc0 .Lpf_last
	global_load_dword v128, v[2:3], off offset:2048
	global_load_dword v129, v[2:3], off offset:2304
	global_load_dword v130, v[2:3], off offset:2560
	global_load_dword v131, v[2:3], off offset:2816
	s_waitcnt vmcnt(4)
	s_branch .Lpf_go

.Lpf_go:
	s_waitcnt lgkmcnt(0)
	v_mov_b32_e32 v59, v132
	v_mov_b32_e32 v60, v133
	v_mov_b32_e32 v61, v134
	v_mov_b32_e32 v2, v135
	v_ashrrev_i32_e32 v3, 31, v59
	v_and_b32_e32 v62, 0xffffff80, v59
	v_ashrrev_i32_e32 v63, 31, v60
	v_ashrrev_i32_e32 v65, 31, v61
	v_and_b32_e32 v3, 0x7fffff80, v3
	v_and_b32_e32 v64, 0xffffff80, v60
	v_and_b32_e32 v66, 0xffffff80, v61
	v_and_b32_e32 v63, 0x7fffff80, v63
	v_and_b32_e32 v65, 0x7fffff80, v65
	v_bitop3_b32 v3, v3, v164, v62 bitop3:0xde
	v_bitop3_b32 v62, v63, v165, v64 bitop3:0xde
	v_bitop3_b32 v63, v65, v164, v66 bitop3:0xde
	v_mov_b32_dpp v65, v3 quad_perm:[1,0,3,2] row_mask:0xf bank_mask:0xf bound_ctrl:1
	v_mov_b32_dpp v66, v62 quad_perm:[1,0,3,2] row_mask:0xf bank_mask:0xf bound_ctrl:1
	v_med3_i32 v3, v3, v65, v100
	v_med3_i32 v62, v62, v66, v100
	v_ashrrev_i32_e32 v67, 31, v2
	v_mov_b32_dpp v65, v3 quad_perm:[2,3,0,1] row_mask:0xf bank_mask:0xf bound_ctrl:1
	v_mov_b32_dpp v66, v62 quad_perm:[2,3,0,1] row_mask:0xf bank_mask:0xf bound_ctrl:1
	v_med3_i32 v3, v3, v65, v101
	v_med3_i32 v62, v62, v66, v101
	v_and_b32_e32 v68, 0xffffff80, v2
	v_mov_b32_dpp v65, v3 quad_perm:[1,0,3,2] row_mask:0xf bank_mask:0xf bound_ctrl:1
	v_mov_b32_dpp v66, v62 quad_perm:[1,0,3,2] row_mask:0xf bank_mask:0xf bound_ctrl:1
	v_med3_i32 v3, v3, v65, v102
	v_and_b32_e32 v67, 0x7fffff80, v67
	v_med3_i32 v62, v62, v66, v102
	v_mov_b32_dpp v65, v3 row_half_mirror row_mask:0xf bank_mask:0xf bound_ctrl:1
	v_bitop3_b32 v64, v67, v165, v68 bitop3:0xde
	v_mov_b32_dpp v66, v62 row_half_mirror row_mask:0xf bank_mask:0xf bound_ctrl:1
	v_mov_b32_dpp v67, v65 quad_perm:[3,2,1,0] row_mask:0xf bank_mask:0xf bound_ctrl:1
	s_nop 0
	v_mov_b32_dpp v65, v66 quad_perm:[3,2,1,0] row_mask:0xf bank_mask:0xf bound_ctrl:1
	v_med3_i32 v3, v3, v67, v103
	v_med3_i32 v62, v62, v65, v103
	s_nop 0
	v_mov_b32_dpp v65, v3 quad_perm:[2,3,0,1] row_mask:0xf bank_mask:0xf bound_ctrl:1
	v_mov_b32_dpp v66, v62 quad_perm:[2,3,0,1] row_mask:0xf bank_mask:0xf bound_ctrl:1
	v_med3_i32 v3, v3, v65, v104
	v_med3_i32 v62, v62, v66, v104
	s_nop 0
	v_mov_b32_dpp v65, v3 quad_perm:[1,0,3,2] row_mask:0xf bank_mask:0xf bound_ctrl:1
	v_mov_b32_dpp v66, v62 quad_perm:[1,0,3,2] row_mask:0xf bank_mask:0xf bound_ctrl:1
	v_med3_i32 v3, v3, v65, v105
	v_med3_i32 v62, v62, v66, v105
	s_nop 0
	v_mov_b32_dpp v65, v3 row_ror:8 row_mask:0xf bank_mask:0xf bound_ctrl:1
	v_mov_b32_dpp v66, v62 row_ror:8 row_mask:0xf bank_mask:0xf bound_ctrl:1
	v_med3_i32 v3, v3, v65, v106
	v_med3_i32 v62, v62, v66, v106
	s_nop 0
	v_mov_b32_dpp v65, v3 row_half_mirror row_mask:0xf bank_mask:0xf bound_ctrl:1
	v_mov_b32_dpp v66, v62 row_half_mirror row_mask:0xf bank_mask:0xf bound_ctrl:1
	s_nop 0
	v_mov_b32_dpp v67, v65 quad_perm:[3,2,1,0] row_mask:0xf bank_mask:0xf bound_ctrl:1
	v_mov_b32_dpp v65, v66 quad_perm:[3,2,1,0] row_mask:0xf bank_mask:0xf bound_ctrl:1
	v_med3_i32 v3, v3, v67, v107
	v_med3_i32 v62, v62, v65, v107
	s_nop 0
	v_mov_b32_dpp v65, v3 quad_perm:[2,3,0,1] row_mask:0xf bank_mask:0xf bound_ctrl:1
	v_mov_b32_dpp v66, v62 quad_perm:[2,3,0,1] row_mask:0xf bank_mask:0xf bound_ctrl:1
	v_med3_i32 v3, v3, v65, v108
	v_med3_i32 v62, v62, v66, v108
	s_nop 0
	v_mov_b32_dpp v65, v3 quad_perm:[1,0,3,2] row_mask:0xf bank_mask:0xf bound_ctrl:1
	v_mov_b32_dpp v66, v62 quad_perm:[1,0,3,2] row_mask:0xf bank_mask:0xf bound_ctrl:1
	v_med3_i32 v3, v3, v65, v109
	v_med3_i32 v62, v62, v66, v109
	v_mov_b32_e32 v65, v3
	v_mov_b32_e32 v66, v3
	v_mov_b32_e32 v67, v62
	v_mov_b32_e32 v68, v62
	v_permlane16_swap_b32_e32 v65, v66
	s_nop 0
	v_permlane16_swap_b32_e32 v67, v68
	v_cndmask_b32_e64 v65, v65, v66, s[6:7]
	v_cndmask_b32_e64 v66, v67, v68, s[6:7]
	v_max_i32_e32 v67, v3, v65
	v_min_i32_e32 v3, v3, v65
	v_cndmask_b32_e64 v3, v3, v67, s[42:43]
	v_med3_i32 v62, v62, v66, v110
	s_nop 0
	v_mov_b32_dpp v65, v3 row_ror:8 row_mask:0xf bank_mask:0xf bound_ctrl:1
	v_mov_b32_dpp v66, v62 row_ror:8 row_mask:0xf bank_mask:0xf bound_ctrl:1
	v_med3_i32 v3, v3, v65, v111
	v_med3_i32 v62, v62, v66, v111
	s_nop 0
	v_mov_b32_dpp v65, v3 row_half_mirror row_mask:0xf bank_mask:0xf bound_ctrl:1
	v_mov_b32_dpp v66, v62 row_half_mirror row_mask:0xf bank_mask:0xf bound_ctrl:1
	s_nop 0
	v_mov_b32_dpp v67, v65 quad_perm:[3,2,1,0] row_mask:0xf bank_mask:0xf bound_ctrl:1
	v_mov_b32_dpp v65, v66 quad_perm:[3,2,1,0] row_mask:0xf bank_mask:0xf bound_ctrl:1
	v_med3_i32 v3, v3, v67, v112
	v_med3_i32 v62, v62, v65, v112
	s_nop 0
	v_mov_b32_dpp v65, v3 quad_perm:[2,3,0,1] row_mask:0xf bank_mask:0xf bound_ctrl:1
	v_med3_i32 v3, v3, v65, v113
	v_mov_b32_dpp v65, v62 quad_perm:[2,3,0,1] row_mask:0xf bank_mask:0xf bound_ctrl:1
	v_med3_i32 v62, v62, v65, v113
	v_mov_b32_dpp v65, v3 quad_perm:[1,0,3,2] row_mask:0xf bank_mask:0xf bound_ctrl:1
	v_med3_i32 v3, v3, v65, v114
	v_mov_b32_dpp v65, v62 quad_perm:[1,0,3,2] row_mask:0xf bank_mask:0xf bound_ctrl:1
	v_med3_i32 v62, v62, v65, v114
	v_mov_b32_e32 v66, v3
	s_nop 1
	v_permlane32_swap_b32_e32 v3, v66
	v_med3_i32 v3, v3, v66, v115
	v_mov_b32_e32 v67, v62
	s_nop 1
	v_permlane32_swap_b32_e32 v62, v67
	v_med3_i32 v62, v62, v67, v116
	v_mov_b32_e32 v66, v3
	s_nop 1
	v_permlane16_swap_b32_e32 v3, v66
	v_med3_i32 v3, v3, v66, v117
	v_mov_b32_e32 v67, v62
	s_nop 1
	v_permlane16_swap_b32_e32 v62, v67
	v_med3_i32 v62, v62, v67, v118
	s_nop 0
	v_mov_b32_dpp v65, v3 row_ror:8 row_mask:0xf bank_mask:0xf bound_ctrl:1
	v_med3_i32 v3, v3, v65, v119
	v_mov_b32_dpp v65, v62 row_ror:8 row_mask:0xf bank_mask:0xf bound_ctrl:1
	v_med3_i32 v62, v62, v65, v120
	v_mov_b32_dpp v65, v3 row_half_mirror row_mask:0xf bank_mask:0xf bound_ctrl:1
	s_nop 0
	v_mov_b32_dpp v66, v62 row_half_mirror row_mask:0xf bank_mask:0xf bound_ctrl:1
	v_mov_b32_dpp v67, v65 quad_perm:[3,2,1,0] row_mask:0xf bank_mask:0xf bound_ctrl:1
	v_med3_i32 v3, v3, v67, v121
	v_mov_b32_dpp v65, v66 quad_perm:[3,2,1,0] row_mask:0xf bank_mask:0xf bound_ctrl:1
	v_med3_i32 v62, v62, v65, v122
	v_mov_b32_dpp v65, v3 quad_perm:[2,3,0,1] row_mask:0xf bank_mask:0xf bound_ctrl:1
	v_med3_i32 v3, v3, v65, v123
	v_mov_b32_dpp v65, v62 quad_perm:[2,3,0,1] row_mask:0xf bank_mask:0xf bound_ctrl:1
	v_med3_i32 v62, v62, v65, v124
	v_mov_b32_dpp v65, v3 quad_perm:[1,0,3,2] row_mask:0xf bank_mask:0xf bound_ctrl:1
	v_med3_i32 v3, v3, v65, v125
	v_mov_b32_dpp v65, v62 quad_perm:[1,0,3,2] row_mask:0xf bank_mask:0xf bound_ctrl:1
	v_med3_i32 v62, v62, v65, v126
	v_max_i32_e32 v3, v3, v62
	v_mov_b32_e32 v65, v3
	s_nop 1
	v_permlane32_swap_b32_e32 v3, v65
	v_med3_i32 v3, v3, v65, v127
	v_mov_b32_e32 v65, v3
	s_nop 1
	v_permlane16_swap_b32_e32 v3, v65
	v_med3_i32 v3, v3, v65, v117
	s_nop 1
	v_mov_b32_dpp v62, v3 row_ror:8 row_mask:0xf bank_mask:0xf bound_ctrl:1
	v_med3_i32 v3, v3, v62, v119
	s_nop 1
	v_mov_b32_dpp v62, v3 row_half_mirror row_mask:0xf bank_mask:0xf bound_ctrl:1
	s_nop 1
	v_mov_b32_dpp v65, v62 quad_perm:[3,2,1,0] row_mask:0xf bank_mask:0xf bound_ctrl:1
	v_med3_i32 v3, v3, v65, v121
	s_nop 1
	v_mov_b32_dpp v62, v3 quad_perm:[2,3,0,1] row_mask:0xf bank_mask:0xf bound_ctrl:1
	v_med3_i32 v3, v3, v62, v123
	s_nop 1
	v_mov_b32_dpp v62, v3 quad_perm:[1,0,3,2] row_mask:0xf bank_mask:0xf bound_ctrl:1
	v_med3_i32 v3, v3, v62, v125
	v_max_i32_dpp v62, v63, v63 quad_perm:[1,0,3,2] row_mask:0xf bank_mask:0xf bound_ctrl:1
	v_min_i32_dpp v63, v63, v63 quad_perm:[1,0,3,2] row_mask:0xf bank_mask:0xf bound_ctrl:1
	v_cndmask_b32_e64 v62, v63, v62, s[12:13]
	s_nop 0
	v_max_i32_dpp v63, v64, v64 quad_perm:[1,0,3,2] row_mask:0xf bank_mask:0xf bound_ctrl:1
	v_min_i32_dpp v64, v64, v64 quad_perm:[1,0,3,2] row_mask:0xf bank_mask:0xf bound_ctrl:1
	v_cndmask_b32_e64 v63, v64, v63, s[12:13]
	s_nop 0
	v_mov_b32_dpp v64, v62 quad_perm:[2,3,0,1] row_mask:0xf bank_mask:0xf bound_ctrl:1
	v_med3_i32 v62, v62, v64, v101
	v_mov_b32_dpp v64, v63 quad_perm:[2,3,0,1] row_mask:0xf bank_mask:0xf bound_ctrl:1
	v_med3_i32 v63, v63, v64, v101
	v_mov_b32_dpp v64, v62 quad_perm:[1,0,3,2] row_mask:0xf bank_mask:0xf bound_ctrl:1
	v_med3_i32 v62, v62, v64, v102
	v_mov_b32_dpp v64, v63 quad_perm:[1,0,3,2] row_mask:0xf bank_mask:0xf bound_ctrl:1
	v_med3_i32 v63, v63, v64, v102
	v_mov_b32_dpp v64, v62 row_half_mirror row_mask:0xf bank_mask:0xf bound_ctrl:1
	s_nop 0
	v_mov_b32_dpp v65, v63 row_half_mirror row_mask:0xf bank_mask:0xf bound_ctrl:1
	v_mov_b32_dpp v66, v64 quad_perm:[3,2,1,0] row_mask:0xf bank_mask:0xf bound_ctrl:1
	v_med3_i32 v62, v62, v66, v103
	v_mov_b32_dpp v64, v65 quad_perm:[3,2,1,0] row_mask:0xf bank_mask:0xf bound_ctrl:1
	v_med3_i32 v63, v63, v64, v103
	v_mov_b32_dpp v64, v62 quad_perm:[2,3,0,1] row_mask:0xf bank_mask:0xf bound_ctrl:1
	v_med3_i32 v62, v62, v64, v104
	v_mov_b32_dpp v64, v63 quad_perm:[2,3,0,1] row_mask:0xf bank_mask:0xf bound_ctrl:1
	v_med3_i32 v63, v63, v64, v104
	v_mov_b32_dpp v64, v62 quad_perm:[1,0,3,2] row_mask:0xf bank_mask:0xf bound_ctrl:1
	v_med3_i32 v62, v62, v64, v105
	v_mov_b32_dpp v64, v63 quad_perm:[1,0,3,2] row_mask:0xf bank_mask:0xf bound_ctrl:1
	v_med3_i32 v63, v63, v64, v105
	v_mov_b32_dpp v64, v62 row_ror:8 row_mask:0xf bank_mask:0xf bound_ctrl:1
	v_med3_i32 v62, v62, v64, v106
	v_mov_b32_dpp v64, v63 row_ror:8 row_mask:0xf bank_mask:0xf bound_ctrl:1
	v_med3_i32 v63, v63, v64, v106
	v_mov_b32_dpp v64, v62 row_half_mirror row_mask:0xf bank_mask:0xf bound_ctrl:1
	s_nop 0
	v_mov_b32_dpp v65, v63 row_half_mirror row_mask:0xf bank_mask:0xf bound_ctrl:1
	v_mov_b32_dpp v66, v64 quad_perm:[3,2,1,0] row_mask:0xf bank_mask:0xf bound_ctrl:1
	v_med3_i32 v62, v62, v66, v107
	v_mov_b32_dpp v64, v65 quad_perm:[3,2,1,0] row_mask:0xf bank_mask:0xf bound_ctrl:1
	v_med3_i32 v63, v63, v64, v107
	v_mov_b32_dpp v64, v62 quad_perm:[2,3,0,1] row_mask:0xf bank_mask:0xf bound_ctrl:1
	v_med3_i32 v62, v62, v64, v108
	v_mov_b32_dpp v64, v63 quad_perm:[2,3,0,1] row_mask:0xf bank_mask:0xf bound_ctrl:1
	v_med3_i32 v63, v63, v64, v108
	v_mov_b32_dpp v64, v62 quad_perm:[1,0,3,2] row_mask:0xf bank_mask:0xf bound_ctrl:1
	v_med3_i32 v62, v62, v64, v109
	v_mov_b32_dpp v64, v63 quad_perm:[1,0,3,2] row_mask:0xf bank_mask:0xf bound_ctrl:1
	v_med3_i32 v63, v63, v64, v109
	v_mov_b32_e32 v65, v62
	s_nop 1
	v_permlane16_swap_b32_e32 v62, v65
	v_med3_i32 v62, v62, v65, v110
	v_mov_b32_e32 v66, v63
	s_nop 1
	v_permlane16_swap_b32_e32 v63, v66
	v_med3_i32 v63, v63, v66, v110
	s_nop 0
	v_mov_b32_dpp v64, v62 row_ror:8 row_mask:0xf bank_mask:0xf bound_ctrl:1
	v_med3_i32 v62, v62, v64, v111
	v_mov_b32_dpp v64, v63 row_ror:8 row_mask:0xf bank_mask:0xf bound_ctrl:1
	v_med3_i32 v63, v63, v64, v111
	v_mov_b32_dpp v64, v62 row_half_mirror row_mask:0xf bank_mask:0xf bound_ctrl:1
	s_nop 0
	v_mov_b32_dpp v65, v63 row_half_mirror row_mask:0xf bank_mask:0xf bound_ctrl:1
	v_mov_b32_dpp v66, v64 quad_perm:[3,2,1,0] row_mask:0xf bank_mask:0xf bound_ctrl:1
	v_med3_i32 v62, v62, v66, v112
	v_mov_b32_dpp v64, v65 quad_perm:[3,2,1,0] row_mask:0xf bank_mask:0xf bound_ctrl:1
	v_med3_i32 v63, v63, v64, v112
	v_mov_b32_dpp v64, v62 quad_perm:[2,3,0,1] row_mask:0xf bank_mask:0xf bound_ctrl:1
	v_med3_i32 v62, v62, v64, v113
	v_mov_b32_dpp v64, v63 quad_perm:[2,3,0,1] row_mask:0xf bank_mask:0xf bound_ctrl:1
	v_med3_i32 v63, v63, v64, v113
	v_mov_b32_dpp v64, v62 quad_perm:[1,0,3,2] row_mask:0xf bank_mask:0xf bound_ctrl:1
	v_med3_i32 v62, v62, v64, v114
	v_mov_b32_dpp v64, v63 quad_perm:[1,0,3,2] row_mask:0xf bank_mask:0xf bound_ctrl:1
	v_med3_i32 v63, v63, v64, v114
	v_mov_b32_e32 v65, v62
	s_nop 1
	v_permlane32_swap_b32_e32 v62, v65
	v_med3_i32 v62, v62, v65, v115
	v_mov_b32_e32 v66, v63
	s_nop 1
	v_permlane32_swap_b32_e32 v63, v66
	v_med3_i32 v63, v63, v66, v116
	v_mov_b32_e32 v65, v62
	s_nop 1
	v_permlane16_swap_b32_e32 v62, v65
	v_med3_i32 v62, v62, v65, v117
	v_mov_b32_e32 v66, v63
	s_nop 1
	v_permlane16_swap_b32_e32 v63, v66
	v_med3_i32 v63, v63, v66, v118
	s_nop 0
	v_mov_b32_dpp v64, v62 row_ror:8 row_mask:0xf bank_mask:0xf bound_ctrl:1
	v_med3_i32 v62, v62, v64, v119
	v_mov_b32_dpp v64, v63 row_ror:8 row_mask:0xf bank_mask:0xf bound_ctrl:1
	v_med3_i32 v63, v63, v64, v120
	v_mov_b32_dpp v64, v62 row_half_mirror row_mask:0xf bank_mask:0xf bound_ctrl:1
	s_nop 0
	v_mov_b32_dpp v65, v63 row_half_mirror row_mask:0xf bank_mask:0xf bound_ctrl:1
	v_mov_b32_dpp v66, v64 quad_perm:[3,2,1,0] row_mask:0xf bank_mask:0xf bound_ctrl:1
	v_med3_i32 v62, v62, v66, v121
	v_mov_b32_dpp v64, v65 quad_perm:[3,2,1,0] row_mask:0xf bank_mask:0xf bound_ctrl:1
	v_med3_i32 v63, v63, v64, v122
	v_mov_b32_dpp v64, v62 quad_perm:[2,3,0,1] row_mask:0xf bank_mask:0xf bound_ctrl:1
	v_med3_i32 v62, v62, v64, v123
	v_mov_b32_dpp v64, v63 quad_perm:[2,3,0,1] row_mask:0xf bank_mask:0xf bound_ctrl:1
	v_med3_i32 v63, v63, v64, v124
	v_mov_b32_dpp v64, v62 quad_perm:[1,0,3,2] row_mask:0xf bank_mask:0xf bound_ctrl:1
	v_med3_i32 v62, v62, v64, v125
	v_mov_b32_dpp v64, v63 quad_perm:[1,0,3,2] row_mask:0xf bank_mask:0xf bound_ctrl:1
	v_med3_i32 v63, v63, v64, v126
	v_max_i32_e32 v62, v62, v63
	v_mov_b32_e32 v64, v62
	s_nop 1
	v_permlane32_swap_b32_e32 v62, v64
	v_med3_i32 v62, v62, v64, v127
	v_mov_b32_e32 v64, v62
	s_nop 1
	v_permlane16_swap_b32_e32 v62, v64
	v_med3_i32 v62, v62, v64, v117
	s_nop 1
	v_mov_b32_dpp v63, v62 row_ror:8 row_mask:0xf bank_mask:0xf bound_ctrl:1
	v_med3_i32 v62, v62, v63, v119
	s_nop 1
	v_mov_b32_dpp v63, v62 row_half_mirror row_mask:0xf bank_mask:0xf bound_ctrl:1
	s_nop 1
	v_mov_b32_dpp v64, v63 quad_perm:[3,2,1,0] row_mask:0xf bank_mask:0xf bound_ctrl:1
	v_med3_i32 v62, v62, v64, v121
	s_nop 1
	v_mov_b32_dpp v63, v62 quad_perm:[2,3,0,1] row_mask:0xf bank_mask:0xf bound_ctrl:1
	v_med3_i32 v62, v62, v63, v123
	s_nop 1
	v_mov_b32_dpp v63, v62 quad_perm:[1,0,3,2] row_mask:0xf bank_mask:0xf bound_ctrl:1
	v_med3_i32 v62, v62, v63, v125
	v_bitop3_b32 v63, v3, s78, v3 bitop3:0xc
	v_bitop3_b32 v3, v3, v166, 63 bitop3:0xce
	v_lshlrev_b32_e32 v3, 2, v3
	ds_bpermute_b32 v59, v3, v59
	ds_bpermute_b32 v3, v3, v60
	v_bitop3_b32 v60, v62, v166, 63 bitop3:0xce
	v_lshlrev_b32_e32 v60, 2, v60
	ds_bpermute_b32 v61, v60, v61
	ds_bpermute_b32 v2, v60, v2
	v_bitop3_b32 v60, v62, s78, v62 bitop3:0xc
	v_cmp_gt_u32_e32 vcc, 64, v63
	s_waitcnt lgkmcnt(2)
	s_nop 0
	v_cndmask_b32_e32 v3, v3, v59, vcc
	v_cmp_gt_u32_e32 vcc, 64, v60
	ds_bpermute_b32 v3, v167, v3
	ds_bpermute_b32 v60, v168, v60
	s_waitcnt lgkmcnt(2)
	v_cndmask_b32_e32 v2, v2, v61, vcc
	ds_bpermute_b32 v2, v168, v2
	s_waitcnt lgkmcnt(0)
	v_add_f32_e32 v2, v3, v2
	v_ashrrev_i32_e32 v3, 31, v2
	v_and_b32_e32 v3, 0x7fffffc0, v3
	v_and_b32_e32 v59, 0xffffffc0, v2
	v_bitop3_b32 v3, v3, v165, v59 bitop3:0xde
	v_cndmask_b32_e64 v3, v3, v173, s[4:5]
	s_nop 1
	v_mov_b32_dpp v59, v3 quad_perm:[1,0,3,2] row_mask:0xf bank_mask:0xf bound_ctrl:1
	v_med3_i32 v3, v3, v59, v100
	s_nop 1
	v_mov_b32_dpp v59, v3 quad_perm:[2,3,0,1] row_mask:0xf bank_mask:0xf bound_ctrl:1
	v_med3_i32 v3, v3, v59, v101
	s_nop 1
	v_mov_b32_dpp v59, v3 quad_perm:[1,0,3,2] row_mask:0xf bank_mask:0xf bound_ctrl:1
	v_med3_i32 v3, v3, v59, v102
	s_nop 1
	v_mov_b32_dpp v59, v3 row_half_mirror row_mask:0xf bank_mask:0xf bound_ctrl:1
	s_nop 1
	v_mov_b32_dpp v61, v59 quad_perm:[3,2,1,0] row_mask:0xf bank_mask:0xf bound_ctrl:1
	v_med3_i32 v3, v3, v61, v103
	s_nop 1
	v_mov_b32_dpp v59, v3 quad_perm:[2,3,0,1] row_mask:0xf bank_mask:0xf bound_ctrl:1
	v_med3_i32 v3, v3, v59, v104
	s_nop 1
	v_mov_b32_dpp v59, v3 quad_perm:[1,0,3,2] row_mask:0xf bank_mask:0xf bound_ctrl:1
	v_med3_i32 v3, v3, v59, v105
	s_nop 1
	v_mov_b32_dpp v59, v3 row_ror:8 row_mask:0xf bank_mask:0xf bound_ctrl:1
	v_med3_i32 v3, v3, v59, v106
	s_nop 1
	v_mov_b32_dpp v59, v3 row_half_mirror row_mask:0xf bank_mask:0xf bound_ctrl:1
	s_nop 1
	v_mov_b32_dpp v61, v59 quad_perm:[3,2,1,0] row_mask:0xf bank_mask:0xf bound_ctrl:1
	v_med3_i32 v3, v3, v61, v107
	s_nop 1
	v_mov_b32_dpp v59, v3 quad_perm:[2,3,0,1] row_mask:0xf bank_mask:0xf bound_ctrl:1
	v_med3_i32 v3, v3, v59, v108
	s_nop 1
	v_mov_b32_dpp v59, v3 quad_perm:[1,0,3,2] row_mask:0xf bank_mask:0xf bound_ctrl:1
	v_med3_i32 v3, v3, v59, v109
	v_mov_b32_e32 v61, v3
	s_nop 1
	v_permlane16_swap_b32_e32 v3, v61
	v_med3_i32 v3, v3, v61, v110
	s_nop 1
	v_mov_b32_dpp v59, v3 row_ror:8 row_mask:0xf bank_mask:0xf bound_ctrl:1
	v_med3_i32 v3, v3, v59, v111
	s_nop 1
	v_mov_b32_dpp v59, v3 row_half_mirror row_mask:0xf bank_mask:0xf bound_ctrl:1
	s_nop 1
	v_mov_b32_dpp v61, v59 quad_perm:[3,2,1,0] row_mask:0xf bank_mask:0xf bound_ctrl:1
	v_med3_i32 v3, v3, v61, v112
	s_nop 1
	v_mov_b32_dpp v59, v3 quad_perm:[2,3,0,1] row_mask:0xf bank_mask:0xf bound_ctrl:1
	v_med3_i32 v3, v3, v59, v113
	s_nop 1
	v_mov_b32_dpp v59, v3 quad_perm:[1,0,3,2] row_mask:0xf bank_mask:0xf bound_ctrl:1
	v_med3_i32 v3, v3, v59, v114
	v_mov_b32_e32 v61, v3
	s_nop 1
	v_permlane32_swap_b32_e32 v3, v61
	v_med3_i32 v3, v3, v61, v127
	v_mov_b32_e32 v61, v3
	s_nop 1
	v_permlane16_swap_b32_e32 v3, v61
	v_med3_i32 v3, v3, v61, v117
	s_nop 1
	v_mov_b32_dpp v59, v3 row_ror:8 row_mask:0xf bank_mask:0xf bound_ctrl:1
	v_med3_i32 v3, v3, v59, v119
	s_nop 1
	v_mov_b32_dpp v59, v3 row_half_mirror row_mask:0xf bank_mask:0xf bound_ctrl:1
	s_nop 1
	v_mov_b32_dpp v61, v59 quad_perm:[3,2,1,0] row_mask:0xf bank_mask:0xf bound_ctrl:1
	v_med3_i32 v3, v3, v61, v121
	s_nop 1
	v_mov_b32_dpp v59, v3 quad_perm:[2,3,0,1] row_mask:0xf bank_mask:0xf bound_ctrl:1
	v_med3_i32 v3, v3, v59, v123
	s_nop 1
	v_mov_b32_dpp v59, v3 quad_perm:[1,0,3,2] row_mask:0xf bank_mask:0xf bound_ctrl:1
	v_med3_i32 v3, v3, v59, v125
	v_and_or_b32 v3, v3, 63, v166
	v_lshlrev_b32_e32 v3, 2, v3
	v_xor_b32_e32 v3, 0xfc, v3
	ds_bpermute_b32 v2, v3, v2
	ds_bpermute_b32 v59, v167, v63
	s_waitcnt lgkmcnt(1)
	v_readlane_b32 s33, v2, 0
	s_nop 1
	v_subrev_f32_e32 v2, s33, v2
	v_mul_f32_e32 v2, v24, v2
	v_mul_f32_e32 v2, 0x3fb8aa3b, v2
	v_exp_f32_e32 v2, v2
	s_waitcnt lgkmcnt(0)
	v_lshl_add_u32 v59, v59, 7, v60
	ds_bpermute_b32 v3, v3, v59
	v_cndmask_b32_e64 v59, 0, v2, s[54:55]
	s_nop 1
	v_add_f32_dpp v59, v59, v59 row_ror:8 row_mask:0xf bank_mask:0xf bound_ctrl:1
	s_nop 1
	v_mov_b32_dpp v60, v59 row_half_mirror row_mask:0xf bank_mask:0xf bound_ctrl:1
	s_nop 1
	v_add_f32_dpp v59, v60, v59 quad_perm:[3,2,1,0] row_mask:0xf bank_mask:0xf bound_ctrl:1
	s_nop 1
	v_add_f32_dpp v59, v59, v59 quad_perm:[2,3,0,1] row_mask:0xf bank_mask:0xf bound_ctrl:1
	s_nop 1
	v_mov_b32_dpp v60, v59 quad_perm:[1,0,3,2] row_mask:0xf bank_mask:0xf bound_ctrl:1
	s_and_saveexec_b64 s[66:67], s[54:55]
	s_cbranch_execz .LBB0_921
	v_add_f32_e32 v59, v59, v60
	v_div_scale_f32 v60, s[68:69], v59, v59, v2
	v_rcp_f32_e32 v61, v60
	v_div_scale_f32 v62, vcc, v2, v59, v2
	v_fma_f32 v63, -v60, v61, 1.0
	v_fmac_f32_e32 v61, v63, v61
	v_mul_f32_e32 v63, v62, v61
	v_fma_f32 v64, -v60, v63, v62
	v_fmac_f32_e32 v63, v64, v61
	v_fma_f32 v60, -v60, v63, v62
	v_div_fmas_f32 v60, v60, v61, v63
	v_div_fixup_f32 v2, v60, v59, v2
	s_waitcnt lgkmcnt(0)
	ds_write2_b32 v28, v3, v2 offset0:16 offset1:144
	s_branch .LBB0_921
